# strategy 6 extended: operand-tile XOR swizzle also in phases D and E
# baseline (speedup 1.0000x reference)
; DI int my_tid() { int t = threadIdx.x; asm volatile("" : "+v"(t)); return t; }
;     ...
;   const int tid = my_tid(), lane = tid & 63, w = __builtin_amdgcn_readfirstlane(tid >> 6), wa = w >> 2, wb = w & 3, qi = lane & 15, quad = lane >> 4;
;   const bf16_t* base = w >= 4 ? Bg : Ag; const int ld = (int)(w >= 4 ? ldb : lda);
;   const bf16_t* nbase = nAg ? (w >= 4 ? nBg : nAg) : base;
;   unsigned off[8];
; #pragma unroll
;   for (int u = 0; u < 8; ++u) {
;     const int blk = (w & 3) * 8 + u, rg = blk >> 1, kh = blk & 1;
;     int R = rg * 16 + (lane >> 2);
;     if (perm) { const int rho = R & 31; R = (R & ~31) + ((rho >> 2) & 3) * 8 + (rho >> 4) * 4 + (rho & 3); }
;     off[u] = (unsigned)(R * ld + kh * 32 + (lane & 3) * 8);
.LBB0_834:
	v_mov_b32_e32 v8, v210
	s_and_b64 s[8:9], s[16:17], exec
	s_mov_b32 s0, 0xc170000
	s_cselect_b32 s36, s33, 0xfd0000
	v_readfirstlane_b32 s38, v8
	s_cselect_b32 s0, s0, 0x13570000
	s_ashr_i32 s27, s38, 6
	s_or_b32 s1, s1, s18
	s_and_b32 s30, s27, 3
	v_lshlrev_b32_e32 v0, 3, v8
	s_cmp_gt_i32 s27, 3
	v_and_b32_e32 v6, 24, v0
	v_lshrrev_b32_e32 v0, 4, v8
	v_sub_u32_e32 v0, 0, v0
	v_and_b32_e32 v0, 3, v0
	v_lshlrev_b32_e32 v0, 3, v0
	v_xor_b32_e32 v6, v6, v0
	v_lshlrev_b32_e32 v0, 7, v8
	s_cselect_b64 s[8:9], -1, 0
	s_lshl_b32 s29, s30, 15
	v_and_b32_e32 v7, 0x1e00, v0
	v_or_b32_e32 v9, s29, v7
	s_cmp_eq_u32 s1, 0
	v_add_u32_e32 v0, v9, v6
	s_mov_b64 s[14:15], -1
	s_cbranch_scc1 .LBB0_836
	s_mov_b64 s[14:15], 0
	v_mov_b64_e32 v[144:145], v[0:1]

;     ...
;   const int ra = (wa * 8) * 2 * 1024 + (qi * 4 + quad) * 16, rb = (wb * 4) * 2 * 1024 + (qi * 4 + quad) * 16;
;   unsigned char* buf0 = lds; unsigned char* buf1 = lds + STAGE_B;
;   const int KT = K >> 6;
;   if (!pre) {
;     g_dma(base, off, 0, buf0, w);
;     asm volatile("s_waitcnt vmcnt(0)" ::: "memory");
;     __syncthreads();
;   }
;   for (int kt = 0; kt < KT; kt += 2) {
;     g_dma(base, off, (kt + 1) * kstep, buf1, w);
;     g_compute(buf0, ra, rb, acc);
.LBB0_838:
	s_or_b64 vcc, s[16:17], s[46:47]
	s_xor_b64 s[0:1], vcc, -1
	s_xor_b64 s[14:15], s[16:17], -1
	s_or_b64 s[0:1], s[16:17], s[0:1]
	s_and_b64 s[40:41], s[16:17], exec
	v_cndmask_b32_e32 v12, v165, v130, vcc
	s_cselect_b32 s36, 0xfd0000, s33
	s_add_u32 s40, s4, s36
	v_ashrrev_i32_e32 v13, 31, v12
	s_addc_u32 s41, s5, 0
	v_lshlrev_b64 v[12:13], 18, v[12:13]
	v_lshl_add_u64 v[12:13], s[40:41], 0, v[12:13]
	s_and_b64 s[40:41], s[16:17], exec
	s_mov_b32 s24, 0xc170000
	v_cndmask_b32_e32 v10, v166, v132, vcc
	s_cselect_b32 s36, 0x13570000, s24
	s_add_u32 s40, s4, s36
	v_ashrrev_i32_e32 v11, 31, v10
	v_cndmask_b32_e64 v0, v4, v12, s[0:1]
	v_cndmask_b32_e64 v9, v5, v13, s[0:1]
	s_addc_u32 s41, s5, 0
	v_lshlrev_b64 v[4:5], 18, v[10:11]
	v_lshl_add_u64 v[4:5], s[40:41], 0, v[4:5]
	v_cndmask_b32_e64 v2, v2, v4, s[0:1]
	v_cndmask_b32_e64 v3, v3, v5, s[0:1]
	v_and_b32_e32 v4, 48, v8
	v_cndmask_b32_e64 v146, v0, v2, s[8:9]
	s_lshl_b32 s0, s38, 6
	v_lshlrev_b32_e32 v0, 6, v8
	s_movk_i32 s1, 0x3c0
	s_and_b32 s0, s0, 0xffffc000
	v_and_or_b32 v0, v0, s1, v4
	v_lshrrev_b32_e32 v4, 2, v8
	v_sub_u32_e32 v4, 0, v4
	v_and_b32_e32 v4, 3, v4
	v_lshlrev_b32_e32 v4, 4, v4
	v_xor_b32_e32 v0, v0, v4
	v_or_b32_e32 v172, s0, v0
	s_add_i32 s0, s29, 0x6020
	v_lshl_or_b32 v173, s30, 13, v0
	v_add_u32_e32 v0, s0, v7
	v_add_lshl_u32 v0, v0, v6, 1
	s_add_i32 s0, s29, 0x6000
	v_lshl_add_u64 v[148:149], v[0:1], 0, s[6:7]
	v_add_u32_e32 v0, s0, v7
	v_add_lshl_u32 v0, v0, v6, 1
	s_add_i32 s0, s29, 0x4020
	v_lshl_add_u64 v[150:151], v[0:1], 0, s[6:7]
	v_add_u32_e32 v0, s0, v7
	v_add_lshl_u32 v0, v0, v6, 1
	s_add_i32 s0, s29, 0x4000
	v_lshl_add_u64 v[152:153], v[0:1], 0, s[6:7]
	v_add_u32_e32 v0, s0, v7
	v_add_lshl_u32 v0, v0, v6, 1
	s_add_i32 s0, s29, 0x2020
	v_lshl_add_u64 v[154:155], v[0:1], 0, s[6:7]
	v_add_u32_e32 v0, s0, v7
	v_add_lshl_u32 v0, v0, v6, 1
	s_add_i32 s0, s29, 0x2000
	v_lshl_add_u64 v[156:157], v[0:1], 0, s[6:7]
	v_add_u32_e32 v0, s0, v7
	v_add_lshl_u32 v0, v0, v6, 1
	v_lshl_add_u64 v[158:159], v[0:1], 0, s[6:7]
	v_add3_u32 v0, s29, 32, v7
	v_add_lshl_u32 v0, v0, v6, 1
	v_lshl_add_u64 v[160:161], v[0:1], 0, s[6:7]
	v_add_u32_e32 v0, s29, v7
	v_add_lshl_u32 v0, v0, v6, 1
	v_mov_b32_e32 v2, 0
	s_mov_b32 s28, 0
	v_cndmask_b32_e64 v131, v9, v3, s[8:9]
	v_lshl_add_u64 v[162:163], v[0:1], 0, s[6:7]
	s_movk_i32 s0, 0x80
	v_mov_b32_e32 v3, v2
	v_mov_b32_e32 v4, v2
	v_mov_b32_e32 v5, v2
	v_mov_b32_e32 v34, v2
	v_mov_b32_e32 v35, v2
	v_mov_b32_e32 v36, v2
	v_mov_b32_e32 v37, v2
	v_mov_b32_e32 v62, v2
	v_mov_b32_e32 v63, v2
	v_mov_b32_e32 v64, v2
	v_mov_b32_e32 v65, v2
	v_mov_b32_e32 v98, v2
	v_mov_b32_e32 v99, v2
	v_mov_b32_e32 v100, v2
	v_mov_b32_e32 v101, v2
	v_mov_b32_e32 v6, v2
	v_mov_b32_e32 v7, v2
	v_mov_b32_e32 v8, v2
	v_mov_b32_e32 v9, v2
	v_mov_b32_e32 v38, v2
	v_mov_b32_e32 v39, v2
	v_mov_b32_e32 v40, v2
	v_mov_b32_e32 v41, v2
	v_mov_b32_e32 v70, v2
	v_mov_b32_e32 v71, v2
	v_mov_b32_e32 v72, v2
	v_mov_b32_e32 v73, v2
	v_mov_b32_e32 v102, v2
	v_mov_b32_e32 v103, v2
	v_mov_b32_e32 v104, v2
	v_mov_b32_e32 v105, v2
	v_mov_b32_e32 v10, v2
	v_mov_b32_e32 v11, v2
	v_mov_b32_e32 v12, v2
	v_mov_b32_e32 v13, v2
	v_mov_b32_e32 v42, v2
	v_mov_b32_e32 v43, v2
	v_mov_b32_e32 v44, v2
	v_mov_b32_e32 v45, v2
	v_mov_b32_e32 v74, v2
	v_mov_b32_e32 v75, v2
	v_mov_b32_e32 v76, v2
	v_mov_b32_e32 v77, v2
	v_mov_b32_e32 v106, v2
	v_mov_b32_e32 v107, v2
	v_mov_b32_e32 v108, v2
	v_mov_b32_e32 v109, v2
	v_mov_b32_e32 v14, v2
	v_mov_b32_e32 v15, v2
	v_mov_b32_e32 v16, v2
	v_mov_b32_e32 v17, v2
	v_mov_b32_e32 v46, v2
	v_mov_b32_e32 v47, v2
	v_mov_b32_e32 v48, v2
	v_mov_b32_e32 v49, v2
	v_mov_b32_e32 v78, v2
	v_mov_b32_e32 v79, v2
	v_mov_b32_e32 v80, v2
	v_mov_b32_e32 v81, v2
	v_mov_b32_e32 v110, v2
	v_mov_b32_e32 v111, v2
	v_mov_b32_e32 v112, v2
	v_mov_b32_e32 v113, v2
	v_mov_b32_e32 v18, v2
	v_mov_b32_e32 v19, v2
	v_mov_b32_e32 v20, v2
	v_mov_b32_e32 v21, v2
	v_mov_b32_e32 v50, v2
	v_mov_b32_e32 v51, v2
	v_mov_b32_e32 v52, v2
	v_mov_b32_e32 v53, v2
	v_mov_b32_e32 v82, v2
	v_mov_b32_e32 v83, v2
	v_mov_b32_e32 v84, v2
	v_mov_b32_e32 v85, v2
	v_mov_b32_e32 v114, v2
	v_mov_b32_e32 v115, v2
	v_mov_b32_e32 v116, v2
	v_mov_b32_e32 v117, v2
	s_waitcnt vmcnt(0)
	v_mov_b32_e32 v22, v2
	v_mov_b32_e32 v23, v2
	v_mov_b32_e32 v24, v2
	v_mov_b32_e32 v25, v2
	v_mov_b32_e32 v54, v2
	v_mov_b32_e32 v55, v2
	v_mov_b32_e32 v56, v2
	v_mov_b32_e32 v57, v2
	v_mov_b32_e32 v86, v2
	v_mov_b32_e32 v87, v2
	v_mov_b32_e32 v88, v2
	v_mov_b32_e32 v89, v2
	v_mov_b32_e32 v118, v2
	v_mov_b32_e32 v119, v2
	v_mov_b32_e32 v120, v2
	v_mov_b32_e32 v121, v2
	v_mov_b32_e32 v26, v2
	v_mov_b32_e32 v27, v2
	v_mov_b32_e32 v28, v2
	v_mov_b32_e32 v29, v2
	v_mov_b32_e32 v58, v2
	v_mov_b32_e32 v59, v2
	v_mov_b32_e32 v60, v2
	v_mov_b32_e32 v61, v2
	v_mov_b32_e32 v90, v2
	v_mov_b32_e32 v91, v2
	v_mov_b32_e32 v92, v2
	v_mov_b32_e32 v93, v2
	v_mov_b32_e32 v122, v2
	v_mov_b32_e32 v123, v2
	v_mov_b32_e32 v124, v2
	v_mov_b32_e32 v125, v2
	v_mov_b32_e32 v30, v2
	v_mov_b32_e32 v31, v2
	v_mov_b32_e32 v32, v2
	v_mov_b32_e32 v33, v2
	v_mov_b32_e32 v66, v2
	v_mov_b32_e32 v67, v2
	v_mov_b32_e32 v68, v2
	v_mov_b32_e32 v69, v2
	v_mov_b32_e32 v94, v2
	v_mov_b32_e32 v95, v2
	v_mov_b32_e32 v96, v2
	v_mov_b32_e32 v97, v2
	v_mov_b32_e32 v126, v2
	v_mov_b32_e32 v127, v2
	v_mov_b32_e32 v128, v2
	v_mov_b32_e32 v129, v2
	v_lshlrev_b32_e32 v152, 1, v133
	v_add_u32_e32 v160, 32, v172
	v_add_u32_e32 v161, 0x10020, v172
	v_add_u32_e32 v162, 0x8020, v173
	v_add_u32_e32 v163, 0x18020, v173
	v_readfirstlane_b32 s38, v142
	v_readfirstlane_b32 s39, v143
	v_readfirstlane_b32 s40, v146
	v_readfirstlane_b32 s41, v131
	v_add_u32_e32 v153, 0x40, v152
	v_add_u32_e32 v154, 0x4000, v152
	v_add_u32_e32 v155, 0x4040, v152
	v_add_u32_e32 v156, 0x8000, v152
	v_add_u32_e32 v157, 0x8040, v152
	v_add_u32_e32 v158, 0xc000, v152
	v_add_u32_e32 v159, 0xc040, v152
	s_add_i32 s42, s27, 32
	s_add_i32 s43, s27, s35
	s_add_u32 s38, s38, 0x80
	s_addc_u32 s39, s39, 0
	s_add_i32 m0, s43, 0x0
	s_nop 0
	global_load_lds_dwordx4 v152, s[38:39]
	s_add_i32 m0, s43, 0x400
	s_nop 0
	global_load_lds_dwordx4 v153, s[38:39]
	s_add_i32 m0, s43, 0x800
	s_nop 0
	global_load_lds_dwordx4 v154, s[38:39]
	s_add_i32 m0, s43, 0xc00
	s_nop 0
	global_load_lds_dwordx4 v155, s[38:39]
	s_add_i32 m0, s43, 0x1000
	s_nop 0
	global_load_lds_dwordx4 v156, s[38:39]
	s_add_i32 m0, s43, 0x1400
	s_nop 0
	global_load_lds_dwordx4 v157, s[38:39]
	s_add_i32 m0, s43, 0x1800
	s_nop 0
	global_load_lds_dwordx4 v158, s[38:39]
	s_add_i32 m0, s43, 0x1c00
	s_nop 0
	global_load_lds_dwordx4 v159, s[38:39]
	s_add_u32 s38, s38, 0x80
	s_addc_u32 s39, s39, 0
	ds_read_b128 v[174:177], v162
	ds_read_b128 v[178:181], v162 offset:2048
	ds_read_b128 v[182:185], v162 offset:4096
	ds_read_b128 v[186:189], v162 offset:6144
	ds_read_b128 v[190:193], v160
	ds_read_b128 v[194:197], v160 offset:2048
	ds_read_b128 v[198:201], v160 offset:4096
	ds_read_b128 v[202:205], v160 offset:6144
	s_mov_b32 s48, 0

;     ...
; #pragma unroll
;   for (int u = 0; u < 8; ++u) {
;     const int blk = (w & 3) * 8 + u, rg = blk >> 1, kh = blk & 1;
;     int R = rg * 16 + (lane >> 2);
;     if (perm) { const int rho = R & 31; R = (R & ~31) + ((rho >> 2) & 3) * 8 + (rho >> 4) * 4 + (rho & 3); }
;     off[u] = (unsigned)(R * ld + kh * 32 + (lane & 3) * 8);
; DI bool tile_order(const Slot sl, int it, int nN, int& mt, int& nt) {
;   const int xcd = sl.xcd, slot = sl.slot, SL = gridDim.x >> 3;
;   const int q = slot + it * SL, per = 8 * nN;
;   if (q >= 2 * per) return false;
;   const int mg = q / per, e = q - mg * per;
;   nt = e >> 3; mt = xcd * 16 + mg * 8 + (e & 7);
;   return true;
; }
.LBB0_961:
	s_add_i32 s27, s28, 1
	s_waitcnt lgkmcnt(0)
	v_mul_lo_u32 v0, s27, v211
	v_add_u32_e32 v160, v0, v212
	v_cmp_gt_i32_e64 s[8:9], 64, v160
	v_cmp_lt_i32_e64 s[10:11], 63, v160
	s_and_saveexec_b64 s[12:13], s[8:9]
	v_ashrrev_i32_e32 v0, 31, v160
	v_lshrrev_b32_e32 v0, 27, v0
	v_add_u32_e32 v0, v160, v0
	v_ashrrev_i32_e32 v3, 5, v0
	v_and_b32_e32 v0, 0xffffffe0, v0
	v_sub_u32_e32 v0, v160, v0
	v_ashrrev_i32_e32 v130, 3, v0
	v_lshl_add_u32 v0, v3, 3, v213
	v_and_or_b32 v132, v160, 7, v0
	s_or_b64 exec, exec, s[12:13]
	v_mov_b32_e32 v8, v210
	s_nop 0
	v_readfirstlane_b32 s36, v8
	s_ashr_i32 s40, s36, 6
	s_and_b32 s30, s40, 3
	v_lshlrev_b32_e32 v0, 3, v8
	s_cmp_gt_i32 s40, 3
	v_and_b32_e32 v6, 24, v0
	v_lshrrev_b32_e32 v0, 4, v8
	v_sub_u32_e32 v0, 0, v0
	v_and_b32_e32 v0, 3, v0
	v_lshlrev_b32_e32 v0, 3, v0
	v_xor_b32_e32 v6, v6, v0
	v_lshlrev_b32_e32 v0, 8, v8
	s_cselect_b64 s[12:13], -1, 0
	s_lshl_b32 s29, s30, 16
	v_and_b32_e32 v7, 0x3c00, v0
	v_or_b32_e32 v9, s29, v7
	s_cmp_eq_u32 s28, 0
	v_add_u32_e32 v0, v9, v6
	s_cbranch_scc1 .LBB0_965
	s_mov_b64 s[38:39], 0
	v_mov_b64_e32 v[140:141], v[0:1]
	s_branch .LBB0_966

;     ...
;   const int ra = (wa * 8) * 2 * 1024 + (qi * 4 + quad) * 16, rb = (wb * 4) * 2 * 1024 + (qi * 4 + quad) * 16;
;   unsigned char* buf0 = lds; unsigned char* buf1 = lds + STAGE_B;
;   const int KT = K >> 6;
;   if (!pre) {
;     g_dma(base, off, 0, buf0, w);
;     asm volatile("s_waitcnt vmcnt(0)" ::: "memory");
;     __syncthreads();
;   }
;   for (int kt = 0; kt < KT; kt += 2) {
;     g_dma(base, off, (kt + 1) * kstep, buf1, w);
;     g_compute(buf0, ra, rb, acc);
.LBB0_968:
	v_ashrrev_i32_e32 v131, 31, v130
	v_lshlrev_b64 v[10:11], 19, v[130:131]
	v_lshl_add_u64 v[10:11], s[0:1], 0, v[10:11]
	v_ashrrev_i32_e32 v133, 31, v132
	v_cndmask_b32_e64 v0, v4, v10, s[8:9]
	v_cndmask_b32_e64 v9, v5, v11, s[8:9]
	v_lshlrev_b64 v[4:5], 19, v[132:133]
	s_and_b64 s[10:11], exec, s[10:11]
	v_lshl_add_u64 v[4:5], s[4:5], 0, v[4:5]
	s_or_b64 s[18:19], s[10:11], s[18:19]
	v_cndmask_b32_e64 v2, v2, v4, s[8:9]
	v_cndmask_b32_e64 v3, v3, v5, s[8:9]
	v_and_b32_e32 v4, 48, v8
	v_cndmask_b32_e64 v142, v0, v2, s[12:13]
	s_lshl_b32 s8, s36, 6
	v_lshlrev_b32_e32 v0, 6, v8
	s_movk_i32 s9, 0x3c0
	s_and_b32 s8, s8, 0xffffc000
	v_and_or_b32 v0, v0, s9, v4
	v_lshrrev_b32_e32 v4, 2, v8
	v_sub_u32_e32 v4, 0, v4
	v_and_b32_e32 v4, 3, v4
	v_lshlrev_b32_e32 v4, 4, v4
	v_xor_b32_e32 v0, v0, v4
	v_or_b32_e32 v133, s8, v0
	s_add_i32 s8, s29, 0xc020
	v_lshl_or_b32 v166, s30, 13, v0
	v_add_u32_e32 v0, s8, v7
	v_add_lshl_u32 v0, v0, v6, 1
	s_add_i32 s8, s29, 0xc000
	v_lshl_add_u64 v[144:145], v[0:1], 0, s[6:7]
	v_add_u32_e32 v0, s8, v7
	v_add_lshl_u32 v0, v0, v6, 1
	s_add_i32 s8, s29, 0x8020
	v_lshl_add_u64 v[146:147], v[0:1], 0, s[6:7]
	v_add_u32_e32 v0, s8, v7
	v_add_lshl_u32 v0, v0, v6, 1
	s_add_i32 s8, s29, 0x8000
	v_lshl_add_u64 v[148:149], v[0:1], 0, s[6:7]
	v_add_u32_e32 v0, s8, v7
	v_add_lshl_u32 v0, v0, v6, 1
	s_add_i32 s8, s29, 0x4020
	v_lshl_add_u64 v[150:151], v[0:1], 0, s[6:7]
	v_add_u32_e32 v0, s8, v7
	v_add_lshl_u32 v0, v0, v6, 1
	s_add_i32 s8, s29, 0x4000
	v_lshl_add_u64 v[152:153], v[0:1], 0, s[6:7]
	v_add_u32_e32 v0, s8, v7
	v_add_lshl_u32 v0, v0, v6, 1
	v_lshl_add_u64 v[154:155], v[0:1], 0, s[6:7]
	v_add3_u32 v0, s29, 32, v7
	v_add_lshl_u32 v0, v0, v6, 1
	v_lshl_add_u64 v[156:157], v[0:1], 0, s[6:7]
	v_add_u32_e32 v0, s29, v7
	v_add_lshl_u32 v0, v0, v6, 1
	v_mov_b32_e32 v2, 0
	v_cndmask_b32_e64 v131, v9, v3, s[12:13]
	v_lshl_add_u64 v[158:159], v[0:1], 0, s[6:7]
	s_mov_b32 s9, 0
	s_movk_i32 s8, 0x80
	v_mov_b32_e32 v3, v2
	v_mov_b32_e32 v4, v2
	v_mov_b32_e32 v5, v2
	v_mov_b32_e32 v26, v2
	v_mov_b32_e32 v27, v2
	v_mov_b32_e32 v28, v2
	v_mov_b32_e32 v29, v2
	v_mov_b32_e32 v58, v2
	v_mov_b32_e32 v59, v2
	v_mov_b32_e32 v60, v2
	v_mov_b32_e32 v61, v2
	v_mov_b32_e32 v90, v2
	v_mov_b32_e32 v91, v2
	v_mov_b32_e32 v92, v2
	v_mov_b32_e32 v93, v2
	v_mov_b32_e32 v6, v2
	v_mov_b32_e32 v7, v2
	v_mov_b32_e32 v8, v2
	v_mov_b32_e32 v9, v2
	v_mov_b32_e32 v38, v2
	v_mov_b32_e32 v39, v2
	v_mov_b32_e32 v40, v2
	v_mov_b32_e32 v41, v2
	v_mov_b32_e32 v70, v2
	v_mov_b32_e32 v71, v2
	v_mov_b32_e32 v72, v2
	v_mov_b32_e32 v73, v2
	v_mov_b32_e32 v102, v2
	v_mov_b32_e32 v103, v2
	v_mov_b32_e32 v104, v2
	v_mov_b32_e32 v105, v2
	v_mov_b32_e32 v10, v2
	v_mov_b32_e32 v11, v2
	v_mov_b32_e32 v12, v2
	v_mov_b32_e32 v13, v2
	v_mov_b32_e32 v42, v2
	v_mov_b32_e32 v43, v2
	v_mov_b32_e32 v44, v2
	v_mov_b32_e32 v45, v2
	v_mov_b32_e32 v74, v2
	v_mov_b32_e32 v75, v2
	v_mov_b32_e32 v76, v2
	v_mov_b32_e32 v77, v2
	v_mov_b32_e32 v106, v2
	v_mov_b32_e32 v107, v2
	v_mov_b32_e32 v108, v2
	v_mov_b32_e32 v109, v2
	v_mov_b32_e32 v14, v2
	v_mov_b32_e32 v15, v2
	v_mov_b32_e32 v16, v2
	v_mov_b32_e32 v17, v2
	v_mov_b32_e32 v46, v2
	v_mov_b32_e32 v47, v2
	v_mov_b32_e32 v48, v2
	v_mov_b32_e32 v49, v2
	v_mov_b32_e32 v78, v2
	v_mov_b32_e32 v79, v2
	v_mov_b32_e32 v80, v2
	v_mov_b32_e32 v81, v2
	v_mov_b32_e32 v110, v2
	v_mov_b32_e32 v111, v2
	v_mov_b32_e32 v112, v2
	v_mov_b32_e32 v113, v2
	v_mov_b32_e32 v18, v2
	v_mov_b32_e32 v19, v2
	v_mov_b32_e32 v20, v2
	v_mov_b32_e32 v21, v2
	v_mov_b32_e32 v50, v2
	v_mov_b32_e32 v51, v2
	v_mov_b32_e32 v52, v2
	v_mov_b32_e32 v53, v2
	v_mov_b32_e32 v82, v2
	v_mov_b32_e32 v83, v2
	v_mov_b32_e32 v84, v2
	v_mov_b32_e32 v85, v2
	v_mov_b32_e32 v114, v2
	v_mov_b32_e32 v115, v2
	v_mov_b32_e32 v116, v2
	v_mov_b32_e32 v117, v2
	s_waitcnt vmcnt(0)
	v_mov_b32_e32 v22, v2
	v_mov_b32_e32 v23, v2
	v_mov_b32_e32 v24, v2
	v_mov_b32_e32 v25, v2
	v_mov_b32_e32 v54, v2
	v_mov_b32_e32 v55, v2
	v_mov_b32_e32 v56, v2
	v_mov_b32_e32 v57, v2
	v_mov_b32_e32 v86, v2
	v_mov_b32_e32 v87, v2
	v_mov_b32_e32 v88, v2
	v_mov_b32_e32 v89, v2
	v_mov_b32_e32 v118, v2
	v_mov_b32_e32 v119, v2
	v_mov_b32_e32 v120, v2
	v_mov_b32_e32 v121, v2
	v_mov_b32_e32 v30, v2
	v_mov_b32_e32 v31, v2
	v_mov_b32_e32 v32, v2
	v_mov_b32_e32 v33, v2
	v_mov_b32_e32 v62, v2
	v_mov_b32_e32 v63, v2
	v_mov_b32_e32 v64, v2
	v_mov_b32_e32 v65, v2
	v_mov_b32_e32 v94, v2
	v_mov_b32_e32 v95, v2
	v_mov_b32_e32 v96, v2
	v_mov_b32_e32 v97, v2
	v_mov_b32_e32 v122, v2
	v_mov_b32_e32 v123, v2
	v_mov_b32_e32 v124, v2
	v_mov_b32_e32 v125, v2
	v_mov_b32_e32 v34, v2
	v_mov_b32_e32 v35, v2
	v_mov_b32_e32 v36, v2
	v_mov_b32_e32 v37, v2
	v_mov_b32_e32 v66, v2
	v_mov_b32_e32 v67, v2
	v_mov_b32_e32 v68, v2
	v_mov_b32_e32 v69, v2
	v_mov_b32_e32 v98, v2
	v_mov_b32_e32 v99, v2
	v_mov_b32_e32 v100, v2
	v_mov_b32_e32 v101, v2
	v_mov_b32_e32 v126, v2
	v_mov_b32_e32 v127, v2
	v_mov_b32_e32 v128, v2
	v_mov_b32_e32 v129, v2
	v_lshlrev_b32_e32 v144, 1, v135
	v_add_u32_e32 v152, 32, v133
	v_add_u32_e32 v153, 0x10020, v133
	v_add_u32_e32 v154, 0x8020, v166
	v_add_u32_e32 v155, 0x18020, v166
	v_readfirstlane_b32 s38, v138
	v_readfirstlane_b32 s39, v139
	v_readfirstlane_b32 s40, v142
	v_readfirstlane_b32 s41, v131
	v_add_u32_e32 v145, 0x40, v144
	v_add_u32_e32 v146, 0x8000, v144
	v_add_u32_e32 v147, 0x8040, v144
	v_add_u32_e32 v148, 0x10000, v144
	v_add_u32_e32 v149, 0x10040, v144
	v_add_u32_e32 v150, 0x18000, v144
	v_add_u32_e32 v151, 0x18040, v144
	s_add_i32 s42, s28, 32
	s_add_i32 s43, s28, s35
	s_add_u32 s38, s38, 0x80
	s_addc_u32 s39, s39, 0
	s_add_i32 m0, s43, 0x0
	s_nop 0
	global_load_lds_dwordx4 v144, s[38:39]
	s_add_i32 m0, s43, 0x400
	s_nop 0
	global_load_lds_dwordx4 v145, s[38:39]
	s_add_i32 m0, s43, 0x800
	s_nop 0
	global_load_lds_dwordx4 v146, s[38:39]
	s_add_i32 m0, s43, 0xc00
	s_nop 0
	global_load_lds_dwordx4 v147, s[38:39]
	s_add_i32 m0, s43, 0x1000
	s_nop 0
	global_load_lds_dwordx4 v148, s[38:39]
	s_add_i32 m0, s43, 0x1400
	s_nop 0
	global_load_lds_dwordx4 v149, s[38:39]
	s_add_i32 m0, s43, 0x1800
	s_nop 0
	global_load_lds_dwordx4 v150, s[38:39]
	s_add_i32 m0, s43, 0x1c00
	s_nop 0
	global_load_lds_dwordx4 v151, s[38:39]
	s_add_u32 s38, s38, 0x80
	s_addc_u32 s39, s39, 0
	ds_read_b128 v[168:171], v154
	ds_read_b128 v[172:175], v154 offset:2048
	ds_read_b128 v[176:179], v154 offset:4096
	ds_read_b128 v[180:183], v154 offset:6144
	ds_read_b128 v[184:187], v152
	ds_read_b128 v[188:191], v152 offset:2048
	ds_read_b128 v[192:195], v152 offset:4096
	ds_read_b128 v[196:199], v152 offset:6144
	s_mov_b32 s46, 0

;     ...
; #pragma unroll
;   for (int u = 0; u < 8; ++u) {
;     const int blk = (w & 3) * 8 + u, rg = blk >> 1, kh = blk & 1;
;     int R = rg * 16 + (lane >> 2);
;     if (perm) { const int rho = R & 31; R = (R & ~31) + ((rho >> 2) & 3) * 8 + (rho >> 4) * 4 + (rho & 3); }
;     off[u] = (unsigned)(R * ld + kh * 32 + (lane & 3) * 8);
; DI bool tile_order(const Slot sl, int it, int nN, int& mt, int& nt) {
;   const int xcd = sl.xcd, slot = sl.slot, SL = gridDim.x >> 3;
;   const int q = slot + it * SL, per = 8 * nN;
;   if (q >= 2 * per) return false;
;   const int mg = q / per, e = q - mg * per;
;   nt = e >> 3; mt = xcd * 16 + mg * 8 + (e & 7);
;   return true;
; }
.LBB0_984:
	s_add_i32 s27, s28, 1
	s_waitcnt lgkmcnt(0)
	v_mul_lo_u32 v0, s27, v211
	v_add_u32_e32 v143, v0, v212
	v_cmp_gt_i32_e64 s[8:9], 64, v143
	v_cmp_lt_i32_e64 s[10:11], 63, v143
	s_and_saveexec_b64 s[12:13], s[8:9]
	v_ashrrev_i32_e32 v0, 31, v143
	v_lshrrev_b32_e32 v0, 27, v0
	v_add_u32_e32 v0, v143, v0
	v_ashrrev_i32_e32 v3, 5, v0
	v_and_b32_e32 v0, 0xffffffe0, v0
	v_sub_u32_e32 v0, v143, v0
	v_ashrrev_i32_e32 v130, 3, v0
	v_lshl_add_u32 v0, v3, 3, v213
	v_and_or_b32 v132, v143, 7, v0
	s_or_b64 exec, exec, s[12:13]
	v_mov_b32_e32 v8, v210
	s_nop 0
	v_readfirstlane_b32 s36, v8
	s_ashr_i32 s40, s36, 6
	s_and_b32 s30, s40, 3
	v_lshlrev_b32_e32 v0, 3, v8
	s_cmp_gt_i32 s40, 3
	v_and_b32_e32 v6, 24, v0
	v_lshrrev_b32_e32 v0, 4, v8
	v_sub_u32_e32 v0, 0, v0
	v_and_b32_e32 v0, 3, v0
	v_lshlrev_b32_e32 v0, 3, v0
	v_xor_b32_e32 v6, v6, v0
	v_lshlrev_b32_e32 v0, 8, v8
	s_cselect_b64 s[12:13], -1, 0
	s_lshl_b32 s29, s30, 16
	v_and_b32_e32 v7, 0x3c00, v0
	v_or_b32_e32 v9, s29, v7
	s_cmp_eq_u32 s28, 0
	v_add_u32_e32 v0, v9, v6
	s_cbranch_scc1 .LBB0_988
	s_mov_b64 s[38:39], 0
	v_mov_b64_e32 v[140:141], v[0:1]
	s_branch .LBB0_989

;     ...
;   const int ra = (wa * 8) * 2 * 1024 + (qi * 4 + quad) * 16, rb = (wb * 4) * 2 * 1024 + (qi * 4 + quad) * 16;
;   unsigned char* buf0 = lds; unsigned char* buf1 = lds + STAGE_B;
;   const int KT = K >> 6;
;   if (!pre) {
;     g_dma(base, off, 0, buf0, w);
;     asm volatile("s_waitcnt vmcnt(0)" ::: "memory");
;     __syncthreads();
;   }
;   for (int kt = 0; kt < KT; kt += 2) {
;     g_dma(base, off, (kt + 1) * kstep, buf1, w);
;     g_compute(buf0, ra, rb, acc);
.LBB0_991:
	v_ashrrev_i32_e32 v131, 31, v130
	v_lshlrev_b64 v[10:11], 19, v[130:131]
	v_lshl_add_u64 v[10:11], s[0:1], 0, v[10:11]
	v_ashrrev_i32_e32 v133, 31, v132
	v_cndmask_b32_e64 v0, v4, v10, s[8:9]
	v_cndmask_b32_e64 v9, v5, v11, s[8:9]
	v_lshlrev_b64 v[4:5], 19, v[132:133]
	s_and_b64 s[10:11], exec, s[10:11]
	v_lshl_add_u64 v[4:5], s[4:5], 0, v[4:5]
	s_or_b64 s[18:19], s[10:11], s[18:19]
	v_cndmask_b32_e64 v2, v2, v4, s[8:9]
	v_cndmask_b32_e64 v3, v3, v5, s[8:9]
	v_and_b32_e32 v4, 48, v8
	v_cndmask_b32_e64 v142, v0, v2, s[12:13]
	s_lshl_b32 s8, s36, 6
	v_lshlrev_b32_e32 v0, 6, v8
	s_movk_i32 s9, 0x3c0
	s_and_b32 s8, s8, 0xffffc000
	v_and_or_b32 v0, v0, s9, v4
	v_lshrrev_b32_e32 v4, 2, v8
	v_sub_u32_e32 v4, 0, v4
	v_and_b32_e32 v4, 3, v4
	v_lshlrev_b32_e32 v4, 4, v4
	v_xor_b32_e32 v0, v0, v4
	v_or_b32_e32 v133, s8, v0
	s_add_i32 s8, s29, 0xc020
	v_lshl_or_b32 v166, s30, 13, v0
	v_add_u32_e32 v0, s8, v7
	v_add_lshl_u32 v0, v0, v6, 1
	s_add_i32 s8, s29, 0xc000
	v_lshl_add_u64 v[144:145], v[0:1], 0, s[6:7]
	v_add_u32_e32 v0, s8, v7
	v_add_lshl_u32 v0, v0, v6, 1
	s_add_i32 s8, s29, 0x8020
	v_lshl_add_u64 v[146:147], v[0:1], 0, s[6:7]
	v_add_u32_e32 v0, s8, v7
	v_add_lshl_u32 v0, v0, v6, 1
	s_add_i32 s8, s29, 0x8000
	v_lshl_add_u64 v[148:149], v[0:1], 0, s[6:7]
	v_add_u32_e32 v0, s8, v7
	v_add_lshl_u32 v0, v0, v6, 1
	s_add_i32 s8, s29, 0x4020
	v_lshl_add_u64 v[150:151], v[0:1], 0, s[6:7]
	v_add_u32_e32 v0, s8, v7
	v_add_lshl_u32 v0, v0, v6, 1
	s_add_i32 s8, s29, 0x4000
	v_lshl_add_u64 v[152:153], v[0:1], 0, s[6:7]
	v_add_u32_e32 v0, s8, v7
	v_add_lshl_u32 v0, v0, v6, 1
	v_lshl_add_u64 v[154:155], v[0:1], 0, s[6:7]
	v_add3_u32 v0, s29, 32, v7
	v_add_lshl_u32 v0, v0, v6, 1
	v_lshl_add_u64 v[156:157], v[0:1], 0, s[6:7]
	v_add_u32_e32 v0, s29, v7
	v_add_lshl_u32 v0, v0, v6, 1
	v_mov_b32_e32 v2, 0
	v_cndmask_b32_e64 v131, v9, v3, s[12:13]
	v_lshl_add_u64 v[158:159], v[0:1], 0, s[6:7]
	s_mov_b32 s9, 0
	s_movk_i32 s8, 0x80
	v_mov_b32_e32 v3, v2
	v_mov_b32_e32 v4, v2
	v_mov_b32_e32 v5, v2
	v_mov_b32_e32 v26, v2
	v_mov_b32_e32 v27, v2
	v_mov_b32_e32 v28, v2
	v_mov_b32_e32 v29, v2
	v_mov_b32_e32 v62, v2
	v_mov_b32_e32 v63, v2
	v_mov_b32_e32 v64, v2
	v_mov_b32_e32 v65, v2
	v_mov_b32_e32 v94, v2
	v_mov_b32_e32 v95, v2
	v_mov_b32_e32 v96, v2
	v_mov_b32_e32 v97, v2
	v_mov_b32_e32 v6, v2
	v_mov_b32_e32 v7, v2
	v_mov_b32_e32 v8, v2
	v_mov_b32_e32 v9, v2
	v_mov_b32_e32 v38, v2
	v_mov_b32_e32 v39, v2
	v_mov_b32_e32 v40, v2
	v_mov_b32_e32 v41, v2
	v_mov_b32_e32 v70, v2
	v_mov_b32_e32 v71, v2
	v_mov_b32_e32 v72, v2
	v_mov_b32_e32 v73, v2
	v_mov_b32_e32 v102, v2
	v_mov_b32_e32 v103, v2
	v_mov_b32_e32 v104, v2
	v_mov_b32_e32 v105, v2
	v_mov_b32_e32 v10, v2
	v_mov_b32_e32 v11, v2
	v_mov_b32_e32 v12, v2
	v_mov_b32_e32 v13, v2
	v_mov_b32_e32 v42, v2
	v_mov_b32_e32 v43, v2
	v_mov_b32_e32 v44, v2
	v_mov_b32_e32 v45, v2
	v_mov_b32_e32 v74, v2
	v_mov_b32_e32 v75, v2
	v_mov_b32_e32 v76, v2
	v_mov_b32_e32 v77, v2
	v_mov_b32_e32 v106, v2
	v_mov_b32_e32 v107, v2
	v_mov_b32_e32 v108, v2
	v_mov_b32_e32 v109, v2
	v_mov_b32_e32 v14, v2
	v_mov_b32_e32 v15, v2
	v_mov_b32_e32 v16, v2
	v_mov_b32_e32 v17, v2
	v_mov_b32_e32 v46, v2
	v_mov_b32_e32 v47, v2
	v_mov_b32_e32 v48, v2
	v_mov_b32_e32 v49, v2
	v_mov_b32_e32 v78, v2
	v_mov_b32_e32 v79, v2
	v_mov_b32_e32 v80, v2
	v_mov_b32_e32 v81, v2
	v_mov_b32_e32 v110, v2
	v_mov_b32_e32 v111, v2
	v_mov_b32_e32 v112, v2
	v_mov_b32_e32 v113, v2
	v_mov_b32_e32 v18, v2
	v_mov_b32_e32 v19, v2
	v_mov_b32_e32 v20, v2
	v_mov_b32_e32 v21, v2
	v_mov_b32_e32 v50, v2
	v_mov_b32_e32 v51, v2
	v_mov_b32_e32 v52, v2
	v_mov_b32_e32 v53, v2
	v_mov_b32_e32 v82, v2
	v_mov_b32_e32 v83, v2
	v_mov_b32_e32 v84, v2
	v_mov_b32_e32 v85, v2
	v_mov_b32_e32 v114, v2
	v_mov_b32_e32 v115, v2
	v_mov_b32_e32 v116, v2
	v_mov_b32_e32 v117, v2
	s_waitcnt vmcnt(0)
	v_mov_b32_e32 v22, v2
	v_mov_b32_e32 v23, v2
	v_mov_b32_e32 v24, v2
	v_mov_b32_e32 v25, v2
	v_mov_b32_e32 v54, v2
	v_mov_b32_e32 v55, v2
	v_mov_b32_e32 v56, v2
	v_mov_b32_e32 v57, v2
	v_mov_b32_e32 v86, v2
	v_mov_b32_e32 v87, v2
	v_mov_b32_e32 v88, v2
	v_mov_b32_e32 v89, v2
	v_mov_b32_e32 v118, v2
	v_mov_b32_e32 v119, v2
	v_mov_b32_e32 v120, v2
	v_mov_b32_e32 v121, v2
	v_mov_b32_e32 v30, v2
	v_mov_b32_e32 v31, v2
	v_mov_b32_e32 v32, v2
	v_mov_b32_e32 v33, v2
	v_mov_b32_e32 v58, v2
	v_mov_b32_e32 v59, v2
	v_mov_b32_e32 v60, v2
	v_mov_b32_e32 v61, v2
	v_mov_b32_e32 v90, v2
	v_mov_b32_e32 v91, v2
	v_mov_b32_e32 v92, v2
	v_mov_b32_e32 v93, v2
	v_mov_b32_e32 v122, v2
	v_mov_b32_e32 v123, v2
	v_mov_b32_e32 v124, v2
	v_mov_b32_e32 v125, v2
	v_mov_b32_e32 v34, v2
	v_mov_b32_e32 v35, v2
	v_mov_b32_e32 v36, v2
	v_mov_b32_e32 v37, v2
	v_mov_b32_e32 v66, v2
	v_mov_b32_e32 v67, v2
	v_mov_b32_e32 v68, v2
	v_mov_b32_e32 v69, v2
	v_mov_b32_e32 v98, v2
	v_mov_b32_e32 v99, v2
	v_mov_b32_e32 v100, v2
	v_mov_b32_e32 v101, v2
	v_mov_b32_e32 v126, v2
	v_mov_b32_e32 v127, v2
	v_mov_b32_e32 v128, v2
	v_mov_b32_e32 v129, v2
	v_lshlrev_b32_e32 v144, 1, v135
	v_add_u32_e32 v152, 32, v133
	v_add_u32_e32 v153, 0x10020, v133
	v_add_u32_e32 v154, 0x8020, v166
	v_add_u32_e32 v155, 0x18020, v166
	v_readfirstlane_b32 s38, v138
	v_readfirstlane_b32 s39, v139
	v_readfirstlane_b32 s40, v142
	v_readfirstlane_b32 s41, v131
	v_add_u32_e32 v145, 0x40, v144
	v_add_u32_e32 v146, 0x8000, v144
	v_add_u32_e32 v147, 0x8040, v144
	v_add_u32_e32 v148, 0x10000, v144
	v_add_u32_e32 v149, 0x10040, v144
	v_add_u32_e32 v150, 0x18000, v144
	v_add_u32_e32 v151, 0x18040, v144
	s_add_i32 s42, s28, 32
	s_add_i32 s43, s28, s35
	s_add_u32 s38, s38, 0x80
	s_addc_u32 s39, s39, 0
	s_add_i32 m0, s43, 0x0
	s_nop 0
	global_load_lds_dwordx4 v144, s[38:39]
	s_add_i32 m0, s43, 0x400
	s_nop 0
	global_load_lds_dwordx4 v145, s[38:39]
	s_add_i32 m0, s43, 0x800
	s_nop 0
	global_load_lds_dwordx4 v146, s[38:39]
	s_add_i32 m0, s43, 0xc00
	s_nop 0
	global_load_lds_dwordx4 v147, s[38:39]
	s_add_i32 m0, s43, 0x1000
	s_nop 0
	global_load_lds_dwordx4 v148, s[38:39]
	s_add_i32 m0, s43, 0x1400
	s_nop 0
	global_load_lds_dwordx4 v149, s[38:39]
	s_add_i32 m0, s43, 0x1800
	s_nop 0
	global_load_lds_dwordx4 v150, s[38:39]
	s_add_i32 m0, s43, 0x1c00
	s_nop 0
	global_load_lds_dwordx4 v151, s[38:39]
	s_add_u32 s38, s38, 0x80
	s_addc_u32 s39, s39, 0
	ds_read_b128 v[168:171], v154
	ds_read_b128 v[172:175], v154 offset:2048
	ds_read_b128 v[176:179], v154 offset:4096
	ds_read_b128 v[180:183], v154 offset:6144
	ds_read_b128 v[184:187], v152
	ds_read_b128 v[188:191], v152 offset:2048
	ds_read_b128 v[192:195], v152 offset:4096
	ds_read_b128 v[196:199], v152 offset:6144
	s_mov_b32 s46, 0
